# GEMM phases: one static s_setprio 1 for the trailing half-workgroup instead of per-MFMA-block priority toggling
# speedup vs baseline: 1.0020x; 1.0020x over previous
; template <class Epi, class Sched, bool ALIGN_EPI = false, bool SP2 = false>
; __device__ __forceinline__ void gemm_phase(PG8_LAS unsigned char* lds, const Gemm g, const Sched& S, const Epi& E, int tid_in) {
;     ...
;     for (;;) {
;         const bool has_next = S.next(ui + 1, nxt);
;         const char* nA = has_next ? (const char*)g.A + (size_t)nxt.pm * tstep : cA; const char* nB = has_next ? (const char*)g.Bt + (size_t)nxt.pn * tstep : cB;
.LBB0_569:
	s_cmp_lt_u32 s74, 4
	s_cbranch_scc1 .Lp1_noprio
	s_setprio 1

; #define PG8_STAGE(bufoff, gbase, voff) do { _Pragma("unroll") for (int _i = 0; _i < 2; ++_i) \
;         __builtin_amdgcn_global_load_lds((const unsigned*)((const char*)(gbase) + (voff)[_i]), (PG8_LAS unsigned*)(lds + (bufoff) + ldsw + _i * 8192), 16, 0, 0); } while (0)
; #define PG8_LDA(dst, b, h) do { _Pragma("unroll") for (int m = 0; m < 4; ++m) _Pragma("unroll") for (int k = 0; k < 2; ++k) dst[m][k] = *(const PG8_LAS bf16x8*)(lds + PG8_SA(b, h) + aoff + m * 2048 + k * 1024); } while (0)
; #define PG8_LDB(dst, b, h) do { _Pragma("unroll") for (int n = 0; n < 2; ++n) _Pragma("unroll") for (int k = 0; k < 2; ++k) dst[n][k] = *(const PG8_LAS bf16x8*)(lds + PG8_SB(b, h) + boff + n * 2048 + k * 1024); } while (0)
; #define PG8_MMA(ai, bj, At, Bt) do { __builtin_amdgcn_s_setprio(1); _Pragma("unroll") for (int m = 0; m < 4; ++m) _Pragma("unroll") for (int n = 0; n < 2; ++n) _Pragma("unroll") for (int k = 0; k < 2; ++k) \
;         acc[ai][bj][m][n] = __builtin_amdgcn_mfma_f32_16x16x32_bf16(Bt[n][k], At[m][k], acc[ai][bj][m][n], 0, 0, 0); __builtin_amdgcn_s_setprio(0); } while (0)
; #define PG8_WAIT_V(n) asm volatile("s_waitcnt vmcnt(" #n ")" ::: "memory")
; #define PG8_WAIT_L(n) asm volatile("s_waitcnt lgkmcnt(" #n ")" ::: "memory")
; #define PG8_BAR __builtin_amdgcn_s_barrier()
; #define PG8_SCHED __builtin_amdgcn_sched_barrier(0)
; template <class Epi, class Sched, bool ALIGN_EPI = false, bool SP2 = false>
; __device__ __forceinline__ void gemm_phase(PG8_LAS unsigned char* lds, const Gemm g, const Sched& S, const Epi& E, int tid_in) {
;     ...
;             PG8_LDB(B0, 0, 0); PG8_LDB(B1, 0, 1); PG8_SCHED; PG8_LDA(At, 0, 0); PG8_STAGE(PG8_SA(1, 1), a1 + hstep, voffA);
;             PG8_WAIT_V(8); PG8_WAIT_L(0); PG8_BAR; PG8_MMA(0, 0, At, B0); PG8_MMA(0, 1, At, B1); PG8_BAR; PG8_SCHED;
;             PG8_LDA(At, 0, 1); PG8_STAGE(PG8_SB(0, 0), b2, voffB); PG8_STAGE(PG8_SB(0, 1), b2 + hstep, voffB); PG8_STAGE(PG8_SA(0, 0), a2, voffA);
;             PG8_WAIT_V(8); PG8_WAIT_L(0); PG8_BAR; PG8_MMA(1, 0, At, B0); PG8_MMA(1, 1, At, B1); PG8_BAR; PG8_SCHED;
.LBB0_577:
	ds_read_b128 v[128:131], v212
	ds_read_b128 v[132:135], v212 offset:1024
	ds_read_b128 v[136:139], v212 offset:2048
	ds_read_b128 v[140:143], v212 offset:3072
	ds_read_b128 v[144:147], v213
	ds_read_b128 v[148:151], v213 offset:1024
	ds_read_b128 v[152:155], v213 offset:2048
	ds_read_b128 v[156:159], v213 offset:3072
	s_add_u32 s8, s6, 0xfff00080
	s_addc_u32 s9, s7, -1
	s_cmp_eq_u32 s43, 60
	s_cselect_b32 s41, s1, s9
	s_cselect_b32 s40, s2, s8
	s_cselect_b32 s9, s5, s42
	s_cselect_b32 s8, s29, s31
	v_lshl_add_u64 v[204:205], s[6:7], 0, v[178:179]
	s_add_i32 m0, s48, 0xc000
	ds_read_b128 v[160:163], v214
	ds_read_b128 v[184:187], v214 offset:1024
	ds_read_b128 v[188:191], v214 offset:2048
	ds_read_b128 v[192:195], v214 offset:3072
	ds_read_b128 v[196:199], v214 offset:4096
	ds_read_b128 v[200:203], v214 offset:5120
	ds_read_b128 v[216:219], v214 offset:6144
	ds_read_b128 v[220:223], v214 offset:7168
	global_load_lds_dwordx4 v[204:205], off
	v_lshl_add_u64 v[204:205], s[6:7], 0, v[180:181]
	s_add_i32 m0, s48, 0xe000
	s_nop 0
	global_load_lds_dwordx4 v[204:205], off
	s_waitcnt vmcnt(8)
	s_waitcnt lgkmcnt(0)
	s_barrier
	s_waitcnt lgkmcnt(0)
	v_mfma_f32_16x16x32_bf16 v[124:127], v[128:131], v[160:163], v[124:127]
	v_mfma_f32_16x16x32_bf16 v[120:123], v[136:139], v[160:163], v[120:123]
	v_mfma_f32_16x16x32_bf16 v[108:111], v[128:131], v[188:191], v[108:111]
	v_mfma_f32_16x16x32_bf16 v[104:107], v[136:139], v[188:191], v[104:107]
	v_mfma_f32_16x16x32_bf16 v[92:95], v[128:131], v[196:199], v[92:95]
	v_mfma_f32_16x16x32_bf16 v[88:91], v[136:139], v[196:199], v[88:91]
	v_mfma_f32_16x16x32_bf16 v[76:79], v[128:131], v[216:219], v[76:79]
	v_mfma_f32_16x16x32_bf16 v[72:75], v[136:139], v[216:219], v[72:75]
	v_mfma_f32_16x16x32_bf16 v[124:127], v[132:135], v[184:187], v[124:127]
	v_mfma_f32_16x16x32_bf16 v[120:123], v[140:143], v[184:187], v[120:123]
	v_mfma_f32_16x16x32_bf16 v[108:111], v[132:135], v[192:195], v[108:111]
	v_mfma_f32_16x16x32_bf16 v[104:107], v[140:143], v[192:195], v[104:107]
	v_mfma_f32_16x16x32_bf16 v[92:95], v[132:135], v[200:203], v[92:95]
	v_mfma_f32_16x16x32_bf16 v[88:91], v[140:143], v[200:203], v[88:91]
	v_mfma_f32_16x16x32_bf16 v[76:79], v[132:135], v[220:223], v[76:79]
	v_mfma_f32_16x16x32_bf16 v[72:75], v[140:143], v[220:223], v[72:75]
	v_mfma_f32_16x16x32_bf16 v[116:119], v[144:147], v[160:163], v[116:119]
	v_mfma_f32_16x16x32_bf16 v[112:115], v[152:155], v[160:163], v[112:115]
	v_mfma_f32_16x16x32_bf16 v[100:103], v[144:147], v[188:191], v[100:103]
	v_mfma_f32_16x16x32_bf16 v[96:99], v[152:155], v[188:191], v[96:99]
	v_mfma_f32_16x16x32_bf16 v[84:87], v[144:147], v[196:199], v[84:87]
	v_mfma_f32_16x16x32_bf16 v[80:83], v[152:155], v[196:199], v[80:83]
	v_mfma_f32_16x16x32_bf16 v[68:71], v[144:147], v[216:219], v[68:71]
	v_mfma_f32_16x16x32_bf16 v[64:67], v[152:155], v[216:219], v[64:67]
	v_mfma_f32_16x16x32_bf16 v[116:119], v[148:151], v[184:187], v[116:119]
	v_mfma_f32_16x16x32_bf16 v[112:115], v[156:159], v[184:187], v[112:115]
	v_mfma_f32_16x16x32_bf16 v[100:103], v[148:151], v[192:195], v[100:103]
	v_mfma_f32_16x16x32_bf16 v[96:99], v[156:159], v[192:195], v[96:99]
	v_mfma_f32_16x16x32_bf16 v[84:87], v[148:151], v[200:203], v[84:87]
	v_mfma_f32_16x16x32_bf16 v[80:83], v[156:159], v[200:203], v[80:83]
	v_mfma_f32_16x16x32_bf16 v[68:71], v[148:151], v[220:223], v[68:71]
	v_mfma_f32_16x16x32_bf16 v[64:67], v[156:159], v[220:223], v[64:67]
	s_barrier
	s_add_i32 s69, s62, s47
	v_lshl_add_u64 v[204:205], s[8:9], 0, v[166:167]
	s_mov_b32 m0, s69
	ds_read_b128 v[160:163], v214 offset:16384
	ds_read_b128 v[184:187], v214 offset:17408
	ds_read_b128 v[188:191], v214 offset:18432
	ds_read_b128 v[192:195], v214 offset:19456
	ds_read_b128 v[196:199], v214 offset:20480
	ds_read_b128 v[200:203], v214 offset:21504
	ds_read_b128 v[216:219], v214 offset:22528
	ds_read_b128 v[220:223], v214 offset:23552
	global_load_lds_dwordx4 v[204:205], off
	s_add_i32 m0, s69, 0x2000
	s_add_u32 s70, s8, 0x100000
	v_lshl_add_u64 v[224:225], s[8:9], 0, v[170:171]
	s_addc_u32 s71, s9, 0
	s_add_i32 s69, s63, s47
	global_load_lds_dwordx4 v[224:225], off
	v_lshl_add_u64 v[226:227], s[70:71], 0, v[166:167]
	s_mov_b32 m0, s69
	v_lshl_add_u64 v[228:229], s[40:41], 0, v[168:169]
	global_load_lds_dwordx4 v[226:227], off
	v_lshl_add_u64 v[226:227], s[70:71], 0, v[170:171]
	s_add_i32 m0, s69, 0x2000
	s_nop 0
	global_load_lds_dwordx4 v[226:227], off
	v_lshl_add_u64 v[226:227], s[40:41], 0, v[164:165]
	s_mov_b32 m0, s48
	s_nop 0
	global_load_lds_dwordx4 v[226:227], off
	s_mov_b32 m0, s49
	s_nop 0
	global_load_lds_dwordx4 v[228:229], off
	s_waitcnt vmcnt(8)
	s_waitcnt lgkmcnt(0)
	s_barrier
; #define PG8_STAGE(bufoff, gbase, voff) do { _Pragma("unroll") for (int _i = 0; _i < 2; ++_i) \
;         __builtin_amdgcn_global_load_lds((const unsigned*)((const char*)(gbase) + (voff)[_i]), (PG8_LAS unsigned*)(lds + (bufoff) + ldsw + _i * 8192), 16, 0, 0); } while (0)
; #define PG8_LDA(dst, b, h) do { _Pragma("unroll") for (int m = 0; m < 4; ++m) _Pragma("unroll") for (int k = 0; k < 2; ++k) dst[m][k] = *(const PG8_LAS bf16x8*)(lds + PG8_SA(b, h) + aoff + m * 2048 + k * 1024); } while (0)
; #define PG8_LDB(dst, b, h) do { _Pragma("unroll") for (int n = 0; n < 2; ++n) _Pragma("unroll") for (int k = 0; k < 2; ++k) dst[n][k] = *(const PG8_LAS bf16x8*)(lds + PG8_SB(b, h) + boff + n * 2048 + k * 1024); } while (0)
; #define PG8_MMA(ai, bj, At, Bt) do { __builtin_amdgcn_s_setprio(1); _Pragma("unroll") for (int m = 0; m < 4; ++m) _Pragma("unroll") for (int n = 0; n < 2; ++n) _Pragma("unroll") for (int k = 0; k < 2; ++k) \
;         acc[ai][bj][m][n] = __builtin_amdgcn_mfma_f32_16x16x32_bf16(Bt[n][k], At[m][k], acc[ai][bj][m][n], 0, 0, 0); __builtin_amdgcn_s_setprio(0); } while (0)
; #define PG8_WAIT_V(n) asm volatile("s_waitcnt vmcnt(" #n ")" ::: "memory")
; #define PG8_WAIT_L(n) asm volatile("s_waitcnt lgkmcnt(" #n ")" ::: "memory")
; #define PG8_BAR __builtin_amdgcn_s_barrier()
; #define PG8_SCHED __builtin_amdgcn_sched_barrier(0)
; template <class Epi, class Sched, bool ALIGN_EPI = false, bool SP2 = false>
; __device__ __forceinline__ void gemm_phase(PG8_LAS unsigned char* lds, const Gemm g, const Sched& S, const Epi& E, int tid_in) {
;     ...
;             PG8_WAIT_V(8); PG8_WAIT_L(0); PG8_BAR; PG8_MMA(1, 0, At, B0); PG8_MMA(1, 1, At, B1); PG8_BAR; PG8_SCHED;
;             PG8_LDB(B0, 1, 0); PG8_LDB(B1, 1, 1); PG8_SCHED; PG8_LDA(At, 1, 0); PG8_STAGE(PG8_SA(0, 1), a2 + hstep, voffA);
;             PG8_WAIT_V(8); PG8_WAIT_L(0); PG8_BAR; PG8_MMA(0, 0, At, B0); PG8_MMA(0, 1, At, B1); PG8_BAR; PG8_SCHED;
;             PG8_LDA(At, 1, 1); PG8_STAGE(PG8_SB(1, 0), b3, voffB); PG8_STAGE(PG8_SB(1, 1), b3 + hstep, voffB); PG8_STAGE(PG8_SA(1, 0), a3, voffA);
;             PG8_WAIT_V(8); PG8_WAIT_L(0); PG8_BAR; PG8_MMA(1, 0, At, B0); PG8_MMA(1, 1, At, B1); PG8_BAR; PG8_SCHED;
	s_waitcnt lgkmcnt(0)
	v_mfma_f32_16x16x32_bf16 v[60:63], v[128:131], v[160:163], v[60:63]
	v_mfma_f32_16x16x32_bf16 v[56:59], v[136:139], v[160:163], v[56:59]
	v_mfma_f32_16x16x32_bf16 v[44:47], v[128:131], v[188:191], v[44:47]
	v_mfma_f32_16x16x32_bf16 v[40:43], v[136:139], v[188:191], v[40:43]
	v_mfma_f32_16x16x32_bf16 v[28:31], v[128:131], v[196:199], v[28:31]
	v_mfma_f32_16x16x32_bf16 v[24:27], v[136:139], v[196:199], v[24:27]
	v_mfma_f32_16x16x32_bf16 v[12:15], v[128:131], v[216:219], v[12:15]
	v_mfma_f32_16x16x32_bf16 v[8:11], v[136:139], v[216:219], v[8:11]
	v_mfma_f32_16x16x32_bf16 v[60:63], v[132:135], v[184:187], v[60:63]
	v_mfma_f32_16x16x32_bf16 v[56:59], v[140:143], v[184:187], v[56:59]
	v_mfma_f32_16x16x32_bf16 v[44:47], v[132:135], v[192:195], v[44:47]
	v_mfma_f32_16x16x32_bf16 v[40:43], v[140:143], v[192:195], v[40:43]
	v_mfma_f32_16x16x32_bf16 v[28:31], v[132:135], v[200:203], v[28:31]
	v_mfma_f32_16x16x32_bf16 v[24:27], v[140:143], v[200:203], v[24:27]
	v_mfma_f32_16x16x32_bf16 v[12:15], v[132:135], v[220:223], v[12:15]
	v_mfma_f32_16x16x32_bf16 v[8:11], v[140:143], v[220:223], v[8:11]
	v_mfma_f32_16x16x32_bf16 v[52:55], v[144:147], v[160:163], v[52:55]
	v_mfma_f32_16x16x32_bf16 v[48:51], v[152:155], v[160:163], v[48:51]
	v_mfma_f32_16x16x32_bf16 v[36:39], v[144:147], v[188:191], v[36:39]
	v_mfma_f32_16x16x32_bf16 v[32:35], v[152:155], v[188:191], v[32:35]
	v_mfma_f32_16x16x32_bf16 v[20:23], v[144:147], v[196:199], v[20:23]
	v_mfma_f32_16x16x32_bf16 v[16:19], v[152:155], v[196:199], v[16:19]
	v_mfma_f32_16x16x32_bf16 v[4:7], v[144:147], v[216:219], v[4:7]
	v_mfma_f32_16x16x32_bf16 v[0:3], v[152:155], v[216:219], v[0:3]
	v_mfma_f32_16x16x32_bf16 v[52:55], v[148:151], v[184:187], v[52:55]
	v_mfma_f32_16x16x32_bf16 v[48:51], v[156:159], v[184:187], v[48:51]
	v_mfma_f32_16x16x32_bf16 v[36:39], v[148:151], v[192:195], v[36:39]
	v_mfma_f32_16x16x32_bf16 v[32:35], v[156:159], v[192:195], v[32:35]
	v_mfma_f32_16x16x32_bf16 v[20:23], v[148:151], v[200:203], v[20:23]
	v_mfma_f32_16x16x32_bf16 v[16:19], v[156:159], v[200:203], v[16:19]
	v_mfma_f32_16x16x32_bf16 v[4:7], v[148:151], v[220:223], v[4:7]
	v_mfma_f32_16x16x32_bf16 v[0:3], v[156:159], v[220:223], v[0:3]
	s_barrier
	s_add_i32 s69, 0, 0x18000
	s_add_i32 s70, 0, 0x1c000
	v_add_u32_e32 v140, s69, v207
	v_add_u32_e32 v156, s70, v207
	ds_read_b128 v[128:131], v140
	ds_read_b128 v[132:135], v140 offset:1024
	ds_read_b128 v[136:139], v140 offset:2048
	ds_read_b128 v[140:143], v140 offset:3072
	ds_read_b128 v[144:147], v156
	ds_read_b128 v[148:151], v156 offset:1024
	ds_read_b128 v[152:155], v156 offset:2048
	ds_read_b128 v[156:159], v156 offset:3072
	s_add_u32 s40, s40, 0x100000
	s_addc_u32 s41, s41, 0
	s_mov_b32 m0, s50
	v_lshl_add_u64 v[230:231], s[40:41], 0, v[164:165]
	ds_read_b128 v[160:163], v214 offset:32768
	ds_read_b128 v[184:187], v214 offset:33792
	ds_read_b128 v[188:191], v214 offset:34816
	ds_read_b128 v[192:195], v214 offset:35840
	ds_read_b128 v[196:199], v214 offset:36864
	ds_read_b128 v[200:203], v214 offset:37888
	ds_read_b128 v[216:219], v214 offset:38912
	ds_read_b128 v[220:223], v214 offset:39936
	global_load_lds_dwordx4 v[230:231], off
	v_lshl_add_u64 v[230:231], s[40:41], 0, v[168:169]
	s_mov_b32 m0, s51
	s_nop 0
	global_load_lds_dwordx4 v[230:231], off
	s_waitcnt vmcnt(8)
	s_waitcnt lgkmcnt(0)
	s_barrier
	s_waitcnt lgkmcnt(0)
	v_mfma_f32_16x16x32_bf16 v[124:127], v[128:131], v[160:163], v[124:127]
	v_mfma_f32_16x16x32_bf16 v[120:123], v[136:139], v[160:163], v[120:123]
	v_mfma_f32_16x16x32_bf16 v[108:111], v[128:131], v[188:191], v[108:111]
	v_mfma_f32_16x16x32_bf16 v[104:107], v[136:139], v[188:191], v[104:107]
	v_mfma_f32_16x16x32_bf16 v[92:95], v[128:131], v[196:199], v[92:95]
	v_mfma_f32_16x16x32_bf16 v[88:91], v[136:139], v[196:199], v[88:91]
	v_mfma_f32_16x16x32_bf16 v[76:79], v[128:131], v[216:219], v[76:79]
	v_mfma_f32_16x16x32_bf16 v[72:75], v[136:139], v[216:219], v[72:75]
	v_mfma_f32_16x16x32_bf16 v[124:127], v[132:135], v[184:187], v[124:127]
	v_mfma_f32_16x16x32_bf16 v[120:123], v[140:143], v[184:187], v[120:123]
	v_mfma_f32_16x16x32_bf16 v[108:111], v[132:135], v[192:195], v[108:111]
	v_mfma_f32_16x16x32_bf16 v[104:107], v[140:143], v[192:195], v[104:107]
	v_mfma_f32_16x16x32_bf16 v[92:95], v[132:135], v[200:203], v[92:95]
	v_mfma_f32_16x16x32_bf16 v[88:91], v[140:143], v[200:203], v[88:91]
	v_mfma_f32_16x16x32_bf16 v[76:79], v[132:135], v[220:223], v[76:79]
	v_mfma_f32_16x16x32_bf16 v[72:75], v[140:143], v[220:223], v[72:75]
	v_mfma_f32_16x16x32_bf16 v[116:119], v[144:147], v[160:163], v[116:119]
	v_mfma_f32_16x16x32_bf16 v[112:115], v[152:155], v[160:163], v[112:115]
	v_mfma_f32_16x16x32_bf16 v[100:103], v[144:147], v[188:191], v[100:103]
	v_mfma_f32_16x16x32_bf16 v[96:99], v[152:155], v[188:191], v[96:99]
	v_mfma_f32_16x16x32_bf16 v[84:87], v[144:147], v[196:199], v[84:87]
	v_mfma_f32_16x16x32_bf16 v[80:83], v[152:155], v[196:199], v[80:83]
	v_mfma_f32_16x16x32_bf16 v[68:71], v[144:147], v[216:219], v[68:71]
	v_mfma_f32_16x16x32_bf16 v[64:67], v[152:155], v[216:219], v[64:67]
	v_mfma_f32_16x16x32_bf16 v[116:119], v[148:151], v[184:187], v[116:119]
	v_mfma_f32_16x16x32_bf16 v[112:115], v[156:159], v[184:187], v[112:115]
	v_mfma_f32_16x16x32_bf16 v[100:103], v[148:151], v[192:195], v[100:103]
	v_mfma_f32_16x16x32_bf16 v[96:99], v[156:159], v[192:195], v[96:99]
	v_mfma_f32_16x16x32_bf16 v[84:87], v[148:151], v[200:203], v[84:87]
	v_mfma_f32_16x16x32_bf16 v[80:83], v[156:159], v[200:203], v[80:83]
	v_mfma_f32_16x16x32_bf16 v[68:71], v[148:151], v[220:223], v[68:71]
	v_mfma_f32_16x16x32_bf16 v[64:67], v[156:159], v[220:223], v[64:67]
	s_barrier
; #define PG8_STAGE(bufoff, gbase, voff) do { _Pragma("unroll") for (int _i = 0; _i < 2; ++_i) \
;         __builtin_amdgcn_global_load_lds((const unsigned*)((const char*)(gbase) + (voff)[_i]), (PG8_LAS unsigned*)(lds + (bufoff) + ldsw + _i * 8192), 16, 0, 0); } while (0)
; #define PG8_LDA(dst, b, h) do { _Pragma("unroll") for (int m = 0; m < 4; ++m) _Pragma("unroll") for (int k = 0; k < 2; ++k) dst[m][k] = *(const PG8_LAS bf16x8*)(lds + PG8_SA(b, h) + aoff + m * 2048 + k * 1024); } while (0)
; #define PG8_MMA(ai, bj, At, Bt) do { __builtin_amdgcn_s_setprio(1); _Pragma("unroll") for (int m = 0; m < 4; ++m) _Pragma("unroll") for (int n = 0; n < 2; ++n) _Pragma("unroll") for (int k = 0; k < 2; ++k) \
;         acc[ai][bj][m][n] = __builtin_amdgcn_mfma_f32_16x16x32_bf16(Bt[n][k], At[m][k], acc[ai][bj][m][n], 0, 0, 0); __builtin_amdgcn_s_setprio(0); } while (0)
; #define PG8_WAIT_V(n) asm volatile("s_waitcnt vmcnt(" #n ")" ::: "memory")
; #define PG8_WAIT_L(n) asm volatile("s_waitcnt lgkmcnt(" #n ")" ::: "memory")
; #define PG8_BAR __builtin_amdgcn_s_barrier()
; #define PG8_SCHED __builtin_amdgcn_sched_barrier(0)
;     __device__ __forceinline__ void operator()(const f32x4 (&acc)[2][2][4][2], const Unit& u, int wr, int wc, int fr, int fq) const {
;         const int pn = u.pn + pn0; const int row0 = u.pm * BM + wr * 64 + fr;
;         if (pn < 16) {
; template <class Epi, class Sched, bool ALIGN_EPI = false, bool SP2 = false>
; __device__ __forceinline__ void gemm_phase(PG8_LAS unsigned char* lds, const Gemm g, const Sched& S, const Epi& E, int tid_in) {
;     ...
;             PG8_LDA(At, 1, 1); PG8_STAGE(PG8_SB(1, 0), b3, voffB); PG8_STAGE(PG8_SB(1, 1), b3 + hstep, voffB); PG8_STAGE(PG8_SA(1, 0), a3, voffA);
;             PG8_WAIT_V(8); PG8_WAIT_L(0); PG8_BAR; PG8_MMA(1, 0, At, B0); PG8_MMA(1, 1, At, B1); PG8_BAR; PG8_SCHED;
	s_add_i32 s40, s69, s47
	v_lshl_add_u64 v[204:205], v[204:205], 0, s[20:21]
	s_mov_b32 m0, s40
	ds_read_b128 v[160:163], v214 offset:49152
	ds_read_b128 v[184:187], v214 offset:50176
	ds_read_b128 v[188:191], v214 offset:51200
	ds_read_b128 v[192:195], v214 offset:52224
	ds_read_b128 v[196:199], v214 offset:53248
	ds_read_b128 v[200:203], v214 offset:54272
	ds_read_b128 v[216:219], v214 offset:55296
	ds_read_b128 v[220:223], v214 offset:56320
	global_load_lds_dwordx4 v[204:205], off
	s_add_i32 m0, s40, 0x2000
	s_add_u32 s8, s8, 0x100080
	v_lshl_add_u64 v[204:205], v[224:225], 0, s[20:21]
	s_addc_u32 s9, s9, 0
	s_add_i32 s40, s70, s47
	global_load_lds_dwordx4 v[204:205], off
	v_lshl_add_u64 v[204:205], s[8:9], 0, v[166:167]
	s_mov_b32 m0, s40
	s_nop 0
	global_load_lds_dwordx4 v[204:205], off
	v_lshl_add_u64 v[204:205], s[8:9], 0, v[170:171]
	s_add_i32 m0, s40, 0x2000
	s_nop 0
	global_load_lds_dwordx4 v[204:205], off
	v_lshl_add_u64 v[204:205], v[226:227], 0, s[20:21]
	s_mov_b32 m0, s58
	s_nop 0
	global_load_lds_dwordx4 v[204:205], off
	v_lshl_add_u64 v[204:205], v[228:229], 0, s[20:21]
	s_mov_b32 m0, s59
	s_nop 0
	global_load_lds_dwordx4 v[204:205], off
	s_waitcnt vmcnt(8)
	s_waitcnt lgkmcnt(0)
	s_barrier
	s_waitcnt lgkmcnt(0)
	v_mfma_f32_16x16x32_bf16 v[60:63], v[128:131], v[160:163], v[60:63]
	v_mfma_f32_16x16x32_bf16 v[56:59], v[136:139], v[160:163], v[56:59]
	v_mfma_f32_16x16x32_bf16 v[44:47], v[128:131], v[188:191], v[44:47]
	v_mfma_f32_16x16x32_bf16 v[40:43], v[136:139], v[188:191], v[40:43]
	v_mfma_f32_16x16x32_bf16 v[28:31], v[128:131], v[196:199], v[28:31]
	v_mfma_f32_16x16x32_bf16 v[24:27], v[136:139], v[196:199], v[24:27]
	v_mfma_f32_16x16x32_bf16 v[12:15], v[128:131], v[216:219], v[12:15]
	v_mfma_f32_16x16x32_bf16 v[8:11], v[136:139], v[216:219], v[8:11]
	v_mfma_f32_16x16x32_bf16 v[60:63], v[132:135], v[184:187], v[60:63]
	v_mfma_f32_16x16x32_bf16 v[56:59], v[140:143], v[184:187], v[56:59]
	v_mfma_f32_16x16x32_bf16 v[44:47], v[132:135], v[192:195], v[44:47]
	v_mfma_f32_16x16x32_bf16 v[40:43], v[140:143], v[192:195], v[40:43]
	v_mfma_f32_16x16x32_bf16 v[28:31], v[132:135], v[200:203], v[28:31]
	v_mfma_f32_16x16x32_bf16 v[24:27], v[140:143], v[200:203], v[24:27]
	v_mfma_f32_16x16x32_bf16 v[12:15], v[132:135], v[220:223], v[12:15]
	v_mfma_f32_16x16x32_bf16 v[8:11], v[140:143], v[220:223], v[8:11]
	v_mfma_f32_16x16x32_bf16 v[52:55], v[144:147], v[160:163], v[52:55]
	v_mfma_f32_16x16x32_bf16 v[48:51], v[152:155], v[160:163], v[48:51]
	v_mfma_f32_16x16x32_bf16 v[36:39], v[144:147], v[188:191], v[36:39]
	v_mfma_f32_16x16x32_bf16 v[32:35], v[152:155], v[188:191], v[32:35]
	v_mfma_f32_16x16x32_bf16 v[20:23], v[144:147], v[196:199], v[20:23]
	v_mfma_f32_16x16x32_bf16 v[16:19], v[152:155], v[196:199], v[16:19]
	v_mfma_f32_16x16x32_bf16 v[4:7], v[144:147], v[216:219], v[4:7]
	v_mfma_f32_16x16x32_bf16 v[0:3], v[152:155], v[216:219], v[0:3]
	v_mfma_f32_16x16x32_bf16 v[52:55], v[148:151], v[184:187], v[52:55]
	v_mfma_f32_16x16x32_bf16 v[48:51], v[156:159], v[184:187], v[48:51]
	v_mfma_f32_16x16x32_bf16 v[36:39], v[148:151], v[192:195], v[36:39]
	v_mfma_f32_16x16x32_bf16 v[32:35], v[156:159], v[192:195], v[32:35]
	v_mfma_f32_16x16x32_bf16 v[20:23], v[148:151], v[200:203], v[20:23]
	v_mfma_f32_16x16x32_bf16 v[16:19], v[156:159], v[200:203], v[16:19]
	v_mfma_f32_16x16x32_bf16 v[4:7], v[148:151], v[220:223], v[4:7]
	v_mfma_f32_16x16x32_bf16 v[0:3], v[156:159], v[220:223], v[0:3]
	s_barrier
	s_add_i32 s43, s43, 2
	s_add_u32 s6, s6, 0x100
	s_addc_u32 s7, s7, 0
	s_add_u32 s31, s31, 0x100
	s_addc_u32 s42, s42, 0
	s_cmp_gt_u32 s43, 61
	s_cbranch_scc0 .LBB0_577
	s_and_b64 vcc, exec, s[22:23]
	s_cbranch_vccnz .LBB0_581
	v_lshl_add_u32 v184, s4, 8, v206
	s_cmp_gt_i32 s0, 15
	s_mov_b64 s[4:5], -1
	s_cbranch_scc1 .LBB0_582

; #define PG8_WAIT_V(n) asm volatile("s_waitcnt vmcnt(" #n ")" ::: "memory")
; #define PG8_BAR __builtin_amdgcn_s_barrier()
; template <class Epi, class Sched, bool ALIGN_EPI = false, bool SP2 = false>
; __device__ __forceinline__ void gemm_phase(PG8_LAS unsigned char* lds, const Gemm g, const Sched& S, const Epi& E, int tid_in) {
;     ...
;     PG8_WAIT_V(0);
;     if constexpr (!ALIGN_EPI) { if (wr == 0) PG8_BAR; }
;     PG8_BAR;
.LBB0_704:
	s_setprio 0
	s_waitcnt vmcnt(0)
	s_barrier

; #define PG8_STAGE(bufoff, gbase, voff) do { _Pragma("unroll") for (int _i = 0; _i < 2; ++_i) \
;         __builtin_amdgcn_global_load_lds((const unsigned*)((const char*)(gbase) + (voff)[_i]), (PG8_LAS unsigned*)(lds + (bufoff) + ldsw + _i * 8192), 16, 0, 0); } while (0)
; #define PG8_LDA(dst, b, h) do { _Pragma("unroll") for (int m = 0; m < 4; ++m) _Pragma("unroll") for (int k = 0; k < 2; ++k) dst[m][k] = *(const PG8_LAS bf16x8*)(lds + PG8_SA(b, h) + aoff + m * 2048 + k * 1024); } while (0)
; #define PG8_LDB(dst, b, h) do { _Pragma("unroll") for (int n = 0; n < 2; ++n) _Pragma("unroll") for (int k = 0; k < 2; ++k) dst[n][k] = *(const PG8_LAS bf16x8*)(lds + PG8_SB(b, h) + boff + n * 2048 + k * 1024); } while (0)
; #define PG8_MMA(ai, bj, At, Bt) do { __builtin_amdgcn_s_setprio(1); _Pragma("unroll") for (int m = 0; m < 4; ++m) _Pragma("unroll") for (int n = 0; n < 2; ++n) _Pragma("unroll") for (int k = 0; k < 2; ++k) \
;         acc[ai][bj][m][n] = __builtin_amdgcn_mfma_f32_16x16x32_bf16(Bt[n][k], At[m][k], acc[ai][bj][m][n], 0, 0, 0); __builtin_amdgcn_s_setprio(0); } while (0)
; #define PG8_WAIT_V(n) asm volatile("s_waitcnt vmcnt(" #n ")" ::: "memory")
; #define PG8_WAIT_L(n) asm volatile("s_waitcnt lgkmcnt(" #n ")" ::: "memory")
; #define PG8_BAR __builtin_amdgcn_s_barrier()
; #define PG8_SCHED __builtin_amdgcn_sched_barrier(0)
; template <class Epi, class Sched, bool ALIGN_EPI = false, bool SP2 = false>
; __device__ __forceinline__ void gemm_phase(PG8_LAS unsigned char* lds, const Gemm g, const Sched& S, const Epi& E, int tid_in) {
;     ...
;             PG8_LDB(B0, 0, 0); PG8_LDB(B1, 0, 1); PG8_SCHED; PG8_LDA(At, 0, 0); PG8_STAGE(PG8_SA(1, 1), a1 + hstep, voffA);
;             PG8_WAIT_V(8); PG8_WAIT_L(0); PG8_BAR; PG8_MMA(0, 0, At, B0); PG8_MMA(0, 1, At, B1); PG8_BAR; PG8_SCHED;
;             PG8_LDA(At, 0, 1); PG8_STAGE(PG8_SB(0, 0), b2, voffB); PG8_STAGE(PG8_SB(0, 1), b2 + hstep, voffB); PG8_STAGE(PG8_SA(0, 0), a2, voffA);
;             PG8_WAIT_V(8); PG8_WAIT_L(0); PG8_BAR; PG8_MMA(1, 0, At, B0); PG8_MMA(1, 1, At, B1); PG8_BAR; PG8_SCHED;
.LBB0_1369:
	ds_read_b128 v[144:147], v153
	ds_read_b128 v[156:159], v153 offset:1024
	ds_read_b128 v[160:163], v153 offset:2048
	ds_read_b128 v[164:167], v153 offset:3072
	ds_read_b128 v[168:171], v154
	ds_read_b128 v[172:175], v154 offset:1024
	ds_read_b128 v[176:179], v154 offset:2048
	ds_read_b128 v[180:183], v154 offset:3072
	s_add_u32 s28, s26, 0xfff00080
	s_addc_u32 s29, s27, -1
	s_cmp_eq_u32 s54, 60
	s_cselect_b32 s31, s2, s29
	s_cselect_b32 s30, s15, s28
	s_cselect_b32 s29, s13, s53
	s_cselect_b32 s28, s23, s25
	v_lshl_add_u64 v[148:149], s[26:27], 0, v[138:139]
	s_add_i32 m0, s37, 0xc000
	ds_read_b128 v[184:187], v155
	ds_read_b128 v[188:191], v155 offset:1024
	ds_read_b128 v[192:195], v155 offset:2048
	ds_read_b128 v[196:199], v155 offset:3072
	ds_read_b128 v[200:203], v155 offset:4096
	ds_read_b128 v[204:207], v155 offset:5120
	ds_read_b128 v[208:211], v155 offset:6144
	ds_read_b128 v[212:215], v155 offset:7168
	global_load_lds_dwordx4 v[148:149], off
	v_lshl_add_u64 v[148:149], s[26:27], 0, v[140:141]
	s_add_i32 m0, s37, 0xe000
	s_nop 0
	global_load_lds_dwordx4 v[148:149], off
	s_waitcnt vmcnt(8)
	s_waitcnt lgkmcnt(0)
	s_barrier
	s_waitcnt lgkmcnt(0)
	v_mfma_f32_16x16x32_bf16 v[124:127], v[144:147], v[184:187], v[124:127]
	v_mfma_f32_16x16x32_bf16 v[120:123], v[160:163], v[184:187], v[120:123]
	v_mfma_f32_16x16x32_bf16 v[108:111], v[144:147], v[192:195], v[108:111]
	v_mfma_f32_16x16x32_bf16 v[104:107], v[160:163], v[192:195], v[104:107]
	v_mfma_f32_16x16x32_bf16 v[92:95], v[144:147], v[200:203], v[92:95]
	v_mfma_f32_16x16x32_bf16 v[88:91], v[160:163], v[200:203], v[88:91]
	v_mfma_f32_16x16x32_bf16 v[76:79], v[144:147], v[208:211], v[76:79]
	v_mfma_f32_16x16x32_bf16 v[72:75], v[160:163], v[208:211], v[72:75]
	v_mfma_f32_16x16x32_bf16 v[124:127], v[156:159], v[188:191], v[124:127]
	v_mfma_f32_16x16x32_bf16 v[120:123], v[164:167], v[188:191], v[120:123]
	v_mfma_f32_16x16x32_bf16 v[108:111], v[156:159], v[196:199], v[108:111]
	v_mfma_f32_16x16x32_bf16 v[104:107], v[164:167], v[196:199], v[104:107]
	v_mfma_f32_16x16x32_bf16 v[92:95], v[156:159], v[204:207], v[92:95]
	v_mfma_f32_16x16x32_bf16 v[88:91], v[164:167], v[204:207], v[88:91]
	v_mfma_f32_16x16x32_bf16 v[76:79], v[156:159], v[212:215], v[76:79]
	v_mfma_f32_16x16x32_bf16 v[72:75], v[164:167], v[212:215], v[72:75]
	v_mfma_f32_16x16x32_bf16 v[116:119], v[168:171], v[184:187], v[116:119]
	v_mfma_f32_16x16x32_bf16 v[112:115], v[176:179], v[184:187], v[112:115]
	v_mfma_f32_16x16x32_bf16 v[100:103], v[168:171], v[192:195], v[100:103]
	v_mfma_f32_16x16x32_bf16 v[96:99], v[176:179], v[192:195], v[96:99]
	v_mfma_f32_16x16x32_bf16 v[84:87], v[168:171], v[200:203], v[84:87]
	v_mfma_f32_16x16x32_bf16 v[80:83], v[176:179], v[200:203], v[80:83]
	v_mfma_f32_16x16x32_bf16 v[68:71], v[168:171], v[208:211], v[68:71]
	v_mfma_f32_16x16x32_bf16 v[64:67], v[176:179], v[208:211], v[64:67]
	v_mfma_f32_16x16x32_bf16 v[116:119], v[172:175], v[188:191], v[116:119]
	v_mfma_f32_16x16x32_bf16 v[112:115], v[180:183], v[188:191], v[112:115]
	v_mfma_f32_16x16x32_bf16 v[100:103], v[172:175], v[196:199], v[100:103]
	v_mfma_f32_16x16x32_bf16 v[96:99], v[180:183], v[196:199], v[96:99]
	v_mfma_f32_16x16x32_bf16 v[84:87], v[172:175], v[204:207], v[84:87]
	v_mfma_f32_16x16x32_bf16 v[80:83], v[180:183], v[204:207], v[80:83]
	v_mfma_f32_16x16x32_bf16 v[68:71], v[172:175], v[212:215], v[68:71]
	v_mfma_f32_16x16x32_bf16 v[64:67], v[180:183], v[212:215], v[64:67]
	s_barrier
	s_add_i32 s55, s46, s36
	v_lshl_add_u64 v[148:149], s[28:29], 0, v[130:131]
	s_mov_b32 m0, s55
	ds_read_b128 v[184:187], v155 offset:16384
	ds_read_b128 v[188:191], v155 offset:17408
	ds_read_b128 v[192:195], v155 offset:18432
	ds_read_b128 v[196:199], v155 offset:19456
	ds_read_b128 v[200:203], v155 offset:20480
	ds_read_b128 v[204:207], v155 offset:21504
	ds_read_b128 v[208:211], v155 offset:22528
	ds_read_b128 v[212:215], v155 offset:23552
	global_load_lds_dwordx4 v[148:149], off
	s_add_i32 m0, s55, 0x2000
	s_add_u32 s56, s28, 0x100000
	v_lshl_add_u64 v[216:217], s[28:29], 0, v[134:135]
	s_addc_u32 s57, s29, 0
	s_add_i32 s55, s47, s36
	global_load_lds_dwordx4 v[216:217], off
	v_lshl_add_u64 v[218:219], s[56:57], 0, v[130:131]
	s_mov_b32 m0, s55
	v_lshl_add_u64 v[220:221], s[30:31], 0, v[132:133]
	global_load_lds_dwordx4 v[218:219], off
	v_lshl_add_u64 v[218:219], s[56:57], 0, v[134:135]
	s_add_i32 m0, s55, 0x2000
	s_nop 0
	global_load_lds_dwordx4 v[218:219], off
	v_lshl_add_u64 v[218:219], s[30:31], 0, v[128:129]
	s_mov_b32 m0, s37
	s_nop 0
	global_load_lds_dwordx4 v[218:219], off
	s_mov_b32 m0, s38
	s_nop 0
	global_load_lds_dwordx4 v[220:221], off
	s_waitcnt vmcnt(8)
	s_waitcnt lgkmcnt(0)
	s_barrier
; #define PG8_STAGE(bufoff, gbase, voff) do { _Pragma("unroll") for (int _i = 0; _i < 2; ++_i) \
;         __builtin_amdgcn_global_load_lds((const unsigned*)((const char*)(gbase) + (voff)[_i]), (PG8_LAS unsigned*)(lds + (bufoff) + ldsw + _i * 8192), 16, 0, 0); } while (0)
; #define PG8_LDA(dst, b, h) do { _Pragma("unroll") for (int m = 0; m < 4; ++m) _Pragma("unroll") for (int k = 0; k < 2; ++k) dst[m][k] = *(const PG8_LAS bf16x8*)(lds + PG8_SA(b, h) + aoff + m * 2048 + k * 1024); } while (0)
; #define PG8_LDB(dst, b, h) do { _Pragma("unroll") for (int n = 0; n < 2; ++n) _Pragma("unroll") for (int k = 0; k < 2; ++k) dst[n][k] = *(const PG8_LAS bf16x8*)(lds + PG8_SB(b, h) + boff + n * 2048 + k * 1024); } while (0)
; #define PG8_MMA(ai, bj, At, Bt) do { __builtin_amdgcn_s_setprio(1); _Pragma("unroll") for (int m = 0; m < 4; ++m) _Pragma("unroll") for (int n = 0; n < 2; ++n) _Pragma("unroll") for (int k = 0; k < 2; ++k) \
;         acc[ai][bj][m][n] = __builtin_amdgcn_mfma_f32_16x16x32_bf16(Bt[n][k], At[m][k], acc[ai][bj][m][n], 0, 0, 0); __builtin_amdgcn_s_setprio(0); } while (0)
; #define PG8_WAIT_V(n) asm volatile("s_waitcnt vmcnt(" #n ")" ::: "memory")
; #define PG8_WAIT_L(n) asm volatile("s_waitcnt lgkmcnt(" #n ")" ::: "memory")
; #define PG8_BAR __builtin_amdgcn_s_barrier()
; #define PG8_SCHED __builtin_amdgcn_sched_barrier(0)
; template <class Epi, class Sched, bool ALIGN_EPI = false, bool SP2 = false>
; __device__ __forceinline__ void gemm_phase(PG8_LAS unsigned char* lds, const Gemm g, const Sched& S, const Epi& E, int tid_in) {
;     ...
;             PG8_LDA(At, 0, 1); PG8_STAGE(PG8_SB(0, 0), b2, voffB); PG8_STAGE(PG8_SB(0, 1), b2 + hstep, voffB); PG8_STAGE(PG8_SA(0, 0), a2, voffA);
;             PG8_WAIT_V(8); PG8_WAIT_L(0); PG8_BAR; PG8_MMA(1, 0, At, B0); PG8_MMA(1, 1, At, B1); PG8_BAR; PG8_SCHED;
;             PG8_LDB(B0, 1, 0); PG8_LDB(B1, 1, 1); PG8_SCHED; PG8_LDA(At, 1, 0); PG8_STAGE(PG8_SA(0, 1), a2 + hstep, voffA);
;             PG8_WAIT_V(8); PG8_WAIT_L(0); PG8_BAR; PG8_MMA(0, 0, At, B0); PG8_MMA(0, 1, At, B1); PG8_BAR; PG8_SCHED;
	s_waitcnt lgkmcnt(0)
	v_mfma_f32_16x16x32_bf16 v[60:63], v[144:147], v[184:187], v[60:63]
	v_mfma_f32_16x16x32_bf16 v[56:59], v[160:163], v[184:187], v[56:59]
	v_mfma_f32_16x16x32_bf16 v[44:47], v[144:147], v[192:195], v[44:47]
	v_mfma_f32_16x16x32_bf16 v[40:43], v[160:163], v[192:195], v[40:43]
	v_mfma_f32_16x16x32_bf16 v[28:31], v[144:147], v[200:203], v[28:31]
	v_mfma_f32_16x16x32_bf16 v[24:27], v[160:163], v[200:203], v[24:27]
	v_mfma_f32_16x16x32_bf16 v[12:15], v[144:147], v[208:211], v[12:15]
	v_mfma_f32_16x16x32_bf16 v[8:11], v[160:163], v[208:211], v[8:11]
	v_mfma_f32_16x16x32_bf16 v[60:63], v[156:159], v[188:191], v[60:63]
	v_mfma_f32_16x16x32_bf16 v[56:59], v[164:167], v[188:191], v[56:59]
	v_mfma_f32_16x16x32_bf16 v[44:47], v[156:159], v[196:199], v[44:47]
	v_mfma_f32_16x16x32_bf16 v[40:43], v[164:167], v[196:199], v[40:43]
	v_mfma_f32_16x16x32_bf16 v[28:31], v[156:159], v[204:207], v[28:31]
	v_mfma_f32_16x16x32_bf16 v[24:27], v[164:167], v[204:207], v[24:27]
	v_mfma_f32_16x16x32_bf16 v[12:15], v[156:159], v[212:215], v[12:15]
	v_mfma_f32_16x16x32_bf16 v[8:11], v[164:167], v[212:215], v[8:11]
	v_mfma_f32_16x16x32_bf16 v[52:55], v[168:171], v[184:187], v[52:55]
	v_mfma_f32_16x16x32_bf16 v[48:51], v[176:179], v[184:187], v[48:51]
	v_mfma_f32_16x16x32_bf16 v[36:39], v[168:171], v[192:195], v[36:39]
	v_mfma_f32_16x16x32_bf16 v[32:35], v[176:179], v[192:195], v[32:35]
	v_mfma_f32_16x16x32_bf16 v[20:23], v[168:171], v[200:203], v[20:23]
	v_mfma_f32_16x16x32_bf16 v[16:19], v[176:179], v[200:203], v[16:19]
	v_mfma_f32_16x16x32_bf16 v[4:7], v[168:171], v[208:211], v[4:7]
	v_mfma_f32_16x16x32_bf16 v[0:3], v[176:179], v[208:211], v[0:3]
	v_mfma_f32_16x16x32_bf16 v[52:55], v[172:175], v[188:191], v[52:55]
	v_mfma_f32_16x16x32_bf16 v[48:51], v[180:183], v[188:191], v[48:51]
	v_mfma_f32_16x16x32_bf16 v[36:39], v[172:175], v[196:199], v[36:39]
	v_mfma_f32_16x16x32_bf16 v[32:35], v[180:183], v[196:199], v[32:35]
	v_mfma_f32_16x16x32_bf16 v[20:23], v[172:175], v[204:207], v[20:23]
	v_mfma_f32_16x16x32_bf16 v[16:19], v[180:183], v[204:207], v[16:19]
	v_mfma_f32_16x16x32_bf16 v[4:7], v[172:175], v[212:215], v[4:7]
	v_mfma_f32_16x16x32_bf16 v[0:3], v[180:183], v[212:215], v[0:3]
	s_barrier
	s_add_i32 s55, 0, 0x18000
	v_add_u32_e32 v136, s55, v151
	s_add_i32 s56, 0, 0x1c000
	ds_read_b128 v[144:147], v136
	ds_read_b128 v[156:159], v136 offset:1024
	ds_read_b128 v[160:163], v136 offset:2048
	ds_read_b128 v[164:167], v136 offset:3072
	v_add_u32_e32 v136, s56, v151
	ds_read_b128 v[168:171], v136
	ds_read_b128 v[172:175], v136 offset:1024
	ds_read_b128 v[176:179], v136 offset:2048
	ds_read_b128 v[180:183], v136 offset:3072
	s_add_u32 s30, s30, 0x100000
	s_addc_u32 s31, s31, 0
	s_mov_b32 m0, s39
	v_lshl_add_u64 v[222:223], s[30:31], 0, v[128:129]
	ds_read_b128 v[184:187], v155 offset:32768
	ds_read_b128 v[188:191], v155 offset:33792
	ds_read_b128 v[192:195], v155 offset:34816
	ds_read_b128 v[196:199], v155 offset:35840
	ds_read_b128 v[200:203], v155 offset:36864
	ds_read_b128 v[204:207], v155 offset:37888
	ds_read_b128 v[208:211], v155 offset:38912
	ds_read_b128 v[212:215], v155 offset:39936
	global_load_lds_dwordx4 v[222:223], off
	v_lshl_add_u64 v[222:223], s[30:31], 0, v[132:133]
	s_mov_b32 m0, s40
	s_nop 0
	global_load_lds_dwordx4 v[222:223], off
	s_waitcnt vmcnt(8)
	s_waitcnt lgkmcnt(0)
	s_barrier
	s_waitcnt lgkmcnt(0)
	v_mfma_f32_16x16x32_bf16 v[124:127], v[144:147], v[184:187], v[124:127]
	v_mfma_f32_16x16x32_bf16 v[120:123], v[160:163], v[184:187], v[120:123]
	v_mfma_f32_16x16x32_bf16 v[108:111], v[144:147], v[192:195], v[108:111]
	v_mfma_f32_16x16x32_bf16 v[104:107], v[160:163], v[192:195], v[104:107]
	v_mfma_f32_16x16x32_bf16 v[92:95], v[144:147], v[200:203], v[92:95]
	v_mfma_f32_16x16x32_bf16 v[88:91], v[160:163], v[200:203], v[88:91]
	v_mfma_f32_16x16x32_bf16 v[76:79], v[144:147], v[208:211], v[76:79]
	v_mfma_f32_16x16x32_bf16 v[72:75], v[160:163], v[208:211], v[72:75]
	v_mfma_f32_16x16x32_bf16 v[124:127], v[156:159], v[188:191], v[124:127]
	v_mfma_f32_16x16x32_bf16 v[120:123], v[164:167], v[188:191], v[120:123]
	v_mfma_f32_16x16x32_bf16 v[108:111], v[156:159], v[196:199], v[108:111]
	v_mfma_f32_16x16x32_bf16 v[104:107], v[164:167], v[196:199], v[104:107]
	v_mfma_f32_16x16x32_bf16 v[92:95], v[156:159], v[204:207], v[92:95]
	v_mfma_f32_16x16x32_bf16 v[88:91], v[164:167], v[204:207], v[88:91]
	v_mfma_f32_16x16x32_bf16 v[76:79], v[156:159], v[212:215], v[76:79]
	v_mfma_f32_16x16x32_bf16 v[72:75], v[164:167], v[212:215], v[72:75]
	v_mfma_f32_16x16x32_bf16 v[116:119], v[168:171], v[184:187], v[116:119]
	v_mfma_f32_16x16x32_bf16 v[112:115], v[176:179], v[184:187], v[112:115]
	v_mfma_f32_16x16x32_bf16 v[100:103], v[168:171], v[192:195], v[100:103]
	v_mfma_f32_16x16x32_bf16 v[96:99], v[176:179], v[192:195], v[96:99]
	v_mfma_f32_16x16x32_bf16 v[84:87], v[168:171], v[200:203], v[84:87]
	v_mfma_f32_16x16x32_bf16 v[80:83], v[176:179], v[200:203], v[80:83]
	v_mfma_f32_16x16x32_bf16 v[68:71], v[168:171], v[208:211], v[68:71]
	v_mfma_f32_16x16x32_bf16 v[64:67], v[176:179], v[208:211], v[64:67]
	v_mfma_f32_16x16x32_bf16 v[116:119], v[172:175], v[188:191], v[116:119]
	v_mfma_f32_16x16x32_bf16 v[112:115], v[180:183], v[188:191], v[112:115]
	v_mfma_f32_16x16x32_bf16 v[100:103], v[172:175], v[196:199], v[100:103]
	v_mfma_f32_16x16x32_bf16 v[96:99], v[180:183], v[196:199], v[96:99]
	v_mfma_f32_16x16x32_bf16 v[84:87], v[172:175], v[204:207], v[84:87]
	v_mfma_f32_16x16x32_bf16 v[80:83], v[180:183], v[204:207], v[80:83]
	v_mfma_f32_16x16x32_bf16 v[68:71], v[172:175], v[212:215], v[68:71]
	v_mfma_f32_16x16x32_bf16 v[64:67], v[180:183], v[212:215], v[64:67]
	s_barrier
; #define PG8_STAGE(bufoff, gbase, voff) do { _Pragma("unroll") for (int _i = 0; _i < 2; ++_i) \
;         __builtin_amdgcn_global_load_lds((const unsigned*)((const char*)(gbase) + (voff)[_i]), (PG8_LAS unsigned*)(lds + (bufoff) + ldsw + _i * 8192), 16, 0, 0); } while (0)
; #define PG8_LDA(dst, b, h) do { _Pragma("unroll") for (int m = 0; m < 4; ++m) _Pragma("unroll") for (int k = 0; k < 2; ++k) dst[m][k] = *(const PG8_LAS bf16x8*)(lds + PG8_SA(b, h) + aoff + m * 2048 + k * 1024); } while (0)
; #define PG8_MMA(ai, bj, At, Bt) do { __builtin_amdgcn_s_setprio(1); _Pragma("unroll") for (int m = 0; m < 4; ++m) _Pragma("unroll") for (int n = 0; n < 2; ++n) _Pragma("unroll") for (int k = 0; k < 2; ++k) \
;         acc[ai][bj][m][n] = __builtin_amdgcn_mfma_f32_16x16x32_bf16(Bt[n][k], At[m][k], acc[ai][bj][m][n], 0, 0, 0); __builtin_amdgcn_s_setprio(0); } while (0)
; #define PG8_WAIT_V(n) asm volatile("s_waitcnt vmcnt(" #n ")" ::: "memory")
; #define PG8_WAIT_L(n) asm volatile("s_waitcnt lgkmcnt(" #n ")" ::: "memory")
; #define PG8_BAR __builtin_amdgcn_s_barrier()
; #define PG8_SCHED __builtin_amdgcn_sched_barrier(0)
; template <class Epi, class Sched, bool ALIGN_EPI = false, bool SP2 = false>
; __device__ __forceinline__ void gemm_phase(PG8_LAS unsigned char* lds, const Gemm g, const Sched& S, const Epi& E, int tid_in) {
;     ...
;             PG8_LDA(At, 1, 1); PG8_STAGE(PG8_SB(1, 0), b3, voffB); PG8_STAGE(PG8_SB(1, 1), b3 + hstep, voffB); PG8_STAGE(PG8_SA(1, 0), a3, voffA);
;             PG8_WAIT_V(8); PG8_WAIT_L(0); PG8_BAR; PG8_MMA(1, 0, At, B0); PG8_MMA(1, 1, At, B1); PG8_BAR; PG8_SCHED;
	s_add_i32 s30, s55, s36
	v_lshl_add_u64 v[148:149], v[148:149], 0, s[6:7]
	s_mov_b32 m0, s30
	ds_read_b128 v[184:187], v155 offset:49152
	ds_read_b128 v[188:191], v155 offset:50176
	ds_read_b128 v[192:195], v155 offset:51200
	ds_read_b128 v[196:199], v155 offset:52224
	ds_read_b128 v[200:203], v155 offset:53248
	ds_read_b128 v[204:207], v155 offset:54272
	ds_read_b128 v[208:211], v155 offset:55296
	ds_read_b128 v[212:215], v155 offset:56320
	global_load_lds_dwordx4 v[148:149], off
	s_add_i32 m0, s30, 0x2000
	s_add_u32 s28, s28, 0x100080
	v_lshl_add_u64 v[148:149], v[216:217], 0, s[6:7]
	s_addc_u32 s29, s29, 0
	s_add_i32 s30, s56, s36
	global_load_lds_dwordx4 v[148:149], off
	v_lshl_add_u64 v[148:149], s[28:29], 0, v[130:131]
	s_mov_b32 m0, s30
	s_nop 0
	global_load_lds_dwordx4 v[148:149], off
	v_lshl_add_u64 v[148:149], s[28:29], 0, v[134:135]
	s_add_i32 m0, s30, 0x2000
	s_nop 0
	global_load_lds_dwordx4 v[148:149], off
	v_lshl_add_u64 v[148:149], v[218:219], 0, s[6:7]
	s_mov_b32 m0, s42
	s_nop 0
	global_load_lds_dwordx4 v[148:149], off
	v_lshl_add_u64 v[148:149], v[220:221], 0, s[6:7]
	s_mov_b32 m0, s44
	s_nop 0
	global_load_lds_dwordx4 v[148:149], off
	s_waitcnt vmcnt(8)
	s_waitcnt lgkmcnt(0)
	s_barrier
	s_waitcnt lgkmcnt(0)
	v_mfma_f32_16x16x32_bf16 v[60:63], v[144:147], v[184:187], v[60:63]
	v_mfma_f32_16x16x32_bf16 v[56:59], v[160:163], v[184:187], v[56:59]
	v_mfma_f32_16x16x32_bf16 v[44:47], v[144:147], v[192:195], v[44:47]
	v_mfma_f32_16x16x32_bf16 v[40:43], v[160:163], v[192:195], v[40:43]
	v_mfma_f32_16x16x32_bf16 v[28:31], v[144:147], v[200:203], v[28:31]
	v_mfma_f32_16x16x32_bf16 v[24:27], v[160:163], v[200:203], v[24:27]
	v_mfma_f32_16x16x32_bf16 v[12:15], v[144:147], v[208:211], v[12:15]
	v_mfma_f32_16x16x32_bf16 v[8:11], v[160:163], v[208:211], v[8:11]
	v_mfma_f32_16x16x32_bf16 v[60:63], v[156:159], v[188:191], v[60:63]
	v_mfma_f32_16x16x32_bf16 v[56:59], v[164:167], v[188:191], v[56:59]
	v_mfma_f32_16x16x32_bf16 v[44:47], v[156:159], v[196:199], v[44:47]
	v_mfma_f32_16x16x32_bf16 v[40:43], v[164:167], v[196:199], v[40:43]
	v_mfma_f32_16x16x32_bf16 v[28:31], v[156:159], v[204:207], v[28:31]
	v_mfma_f32_16x16x32_bf16 v[24:27], v[164:167], v[204:207], v[24:27]
	v_mfma_f32_16x16x32_bf16 v[12:15], v[156:159], v[212:215], v[12:15]
	v_mfma_f32_16x16x32_bf16 v[8:11], v[164:167], v[212:215], v[8:11]
	v_mfma_f32_16x16x32_bf16 v[52:55], v[168:171], v[184:187], v[52:55]
	v_mfma_f32_16x16x32_bf16 v[48:51], v[176:179], v[184:187], v[48:51]
	v_mfma_f32_16x16x32_bf16 v[36:39], v[168:171], v[192:195], v[36:39]
	v_mfma_f32_16x16x32_bf16 v[32:35], v[176:179], v[192:195], v[32:35]
	v_mfma_f32_16x16x32_bf16 v[20:23], v[168:171], v[200:203], v[20:23]
	v_mfma_f32_16x16x32_bf16 v[16:19], v[176:179], v[200:203], v[16:19]
	v_mfma_f32_16x16x32_bf16 v[4:7], v[168:171], v[208:211], v[4:7]
	v_mfma_f32_16x16x32_bf16 v[0:3], v[176:179], v[208:211], v[0:3]
	v_mfma_f32_16x16x32_bf16 v[52:55], v[172:175], v[188:191], v[52:55]
	v_mfma_f32_16x16x32_bf16 v[48:51], v[180:183], v[188:191], v[48:51]
	v_mfma_f32_16x16x32_bf16 v[36:39], v[172:175], v[196:199], v[36:39]
	v_mfma_f32_16x16x32_bf16 v[32:35], v[180:183], v[196:199], v[32:35]
	v_mfma_f32_16x16x32_bf16 v[20:23], v[172:175], v[204:207], v[20:23]
	v_mfma_f32_16x16x32_bf16 v[16:19], v[180:183], v[204:207], v[16:19]
	v_mfma_f32_16x16x32_bf16 v[4:7], v[172:175], v[212:215], v[4:7]
	v_mfma_f32_16x16x32_bf16 v[0:3], v[180:183], v[212:215], v[0:3]
	s_barrier
	s_add_i32 s54, s54, 2
	s_add_u32 s26, s26, 0x100
	s_addc_u32 s27, s27, 0
	s_add_u32 s25, s25, 0x100
	s_addc_u32 s53, s53, 0
	s_cmp_gt_u32 s54, 61
	s_cbranch_scc0 .LBB0_1369
	s_and_b64 vcc, exec, s[8:9]
	s_cbranch_vccz .LBB0_1372
	s_barrier

; #define PG8_WAIT_V(n) asm volatile("s_waitcnt vmcnt(" #n ")" ::: "memory")
; #define PG8_BAR __builtin_amdgcn_s_barrier()
; template <class Epi, class Sched, bool ALIGN_EPI = false, bool SP2 = false>
; __device__ __forceinline__ void gemm_phase(PG8_LAS unsigned char* lds, const Gemm g, const Sched& S, const Epi& E, int tid_in) {
;     ...
;     PG8_WAIT_V(0);
;     if constexpr (!ALIGN_EPI) { if (wr == 0) PG8_BAR; }
;     PG8_BAR;
.LBB0_1407:
	s_setprio 0
	v_readlane_b32 s52, v253, 46
	s_waitcnt vmcnt(0)
	v_readlane_b32 s56, v253, 50
	v_readlane_b32 s57, v253, 51
	v_readlane_b32 s66, v253, 60
	v_readlane_b32 s67, v253, 61
	v_readlane_b32 s53, v253, 47
	v_readlane_b32 s54, v253, 48
	v_readlane_b32 s55, v253, 49
	v_readlane_b32 s64, v253, 58
	v_readlane_b32 s65, v253, 59
	s_mov_b64 s[84:85], s[56:57]
	s_mov_b64 s[94:95], s[66:67]
	s_mov_b64 s[82:83], s[54:55]
	s_mov_b64 s[80:81], s[52:53]
	s_mov_b64 s[92:93], s[64:65]
	s_barrier
	v_readlane_b32 s58, v253, 52
	v_readlane_b32 s59, v253, 53
	v_readlane_b32 s60, v253, 54
	v_readlane_b32 s61, v253, 55
	v_readlane_b32 s62, v253, 56
	v_readlane_b32 s63, v253, 57

; #define PG8_STAGE(bufoff, gbase, voff) do { _Pragma("unroll") for (int _i = 0; _i < 2; ++_i) \
;         __builtin_amdgcn_global_load_lds((const unsigned*)((const char*)(gbase) + (voff)[_i]), (PG8_LAS unsigned*)(lds + (bufoff) + ldsw + _i * 8192), 16, 0, 0); } while (0)
; #define PG8_LDA(dst, b, h) do { _Pragma("unroll") for (int m = 0; m < 4; ++m) _Pragma("unroll") for (int k = 0; k < 2; ++k) dst[m][k] = *(const PG8_LAS bf16x8*)(lds + PG8_SA(b, h) + aoff + m * 2048 + k * 1024); } while (0)
; #define PG8_LDB(dst, b, h) do { _Pragma("unroll") for (int n = 0; n < 2; ++n) _Pragma("unroll") for (int k = 0; k < 2; ++k) dst[n][k] = *(const PG8_LAS bf16x8*)(lds + PG8_SB(b, h) + boff + n * 2048 + k * 1024); } while (0)
; #define PG8_MMA(ai, bj, At, Bt) do { __builtin_amdgcn_s_setprio(1); _Pragma("unroll") for (int m = 0; m < 4; ++m) _Pragma("unroll") for (int n = 0; n < 2; ++n) _Pragma("unroll") for (int k = 0; k < 2; ++k) \
;         acc[ai][bj][m][n] = __builtin_amdgcn_mfma_f32_16x16x32_bf16(Bt[n][k], At[m][k], acc[ai][bj][m][n], 0, 0, 0); __builtin_amdgcn_s_setprio(0); } while (0)
; #define PG8_WAIT_V(n) asm volatile("s_waitcnt vmcnt(" #n ")" ::: "memory")
; #define PG8_WAIT_L(n) asm volatile("s_waitcnt lgkmcnt(" #n ")" ::: "memory")
; #define PG8_BAR __builtin_amdgcn_s_barrier()
; #define PG8_SCHED __builtin_amdgcn_sched_barrier(0)
; template <class Epi, class Sched, bool ALIGN_EPI = false, bool SP2 = false>
; __device__ __forceinline__ void gemm_phase(PG8_LAS unsigned char* lds, const Gemm g, const Sched& S, const Epi& E, int tid_in) {
;     ...
;             PG8_LDB(B0, 0, 0); PG8_LDB(B1, 0, 1); PG8_SCHED; PG8_LDA(At, 0, 0); PG8_STAGE(PG8_SA(1, 1), a1 + hstep, voffA);
;             PG8_WAIT_V(8); PG8_WAIT_L(0); PG8_BAR; PG8_MMA(0, 0, At, B0); PG8_MMA(0, 1, At, B1); PG8_BAR; PG8_SCHED;
;             PG8_LDA(At, 0, 1); PG8_STAGE(PG8_SB(0, 0), b2, voffB); PG8_STAGE(PG8_SB(0, 1), b2 + hstep, voffB); PG8_STAGE(PG8_SA(0, 0), a2, voffA);
;             PG8_WAIT_V(8); PG8_WAIT_L(0); PG8_BAR; PG8_MMA(1, 0, At, B0); PG8_MMA(1, 1, At, B1); PG8_BAR; PG8_SCHED;
.LBB0_1551:
	ds_read_b128 v[150:153], v147
	ds_read_b128 v[154:157], v147 offset:1024
	ds_read_b128 v[158:161], v147 offset:2048
	ds_read_b128 v[162:165], v147 offset:3072
	ds_read_b128 v[166:169], v148
	ds_read_b128 v[170:173], v148 offset:1024
	ds_read_b128 v[174:177], v148 offset:2048
	ds_read_b128 v[178:181], v148 offset:3072
	s_add_u32 s34, s30, 0xfff00080
	s_addc_u32 s35, s31, -1
	s_cmp_eq_u32 s60, 60
	s_cselect_b32 s37, s21, s35
	s_cselect_b32 s36, s56, s34
	s_cselect_b32 s35, s19, s59
	s_cselect_b32 s34, s57, s58
	v_lshl_add_u64 v[142:143], s[30:31], 0, v[136:137]
	s_add_i32 m0, s29, 0xc000
	ds_read_b128 v[182:185], v149
	ds_read_b128 v[186:189], v149 offset:1024
	ds_read_b128 v[190:193], v149 offset:2048
	ds_read_b128 v[194:197], v149 offset:3072
	ds_read_b128 v[198:201], v149 offset:4096
	ds_read_b128 v[202:205], v149 offset:5120
	ds_read_b128 v[206:209], v149 offset:6144
	ds_read_b128 v[210:213], v149 offset:7168
	global_load_lds_dwordx4 v[142:143], off
	v_lshl_add_u64 v[142:143], s[30:31], 0, v[138:139]
	s_add_i32 m0, s29, 0xe000
	s_nop 0
	global_load_lds_dwordx4 v[142:143], off
	s_waitcnt vmcnt(8)
	s_waitcnt lgkmcnt(0)
	s_barrier
	s_waitcnt lgkmcnt(0)
	v_mfma_f32_16x16x32_bf16 v[124:127], v[150:153], v[182:185], v[124:127]
	v_mfma_f32_16x16x32_bf16 v[120:123], v[158:161], v[182:185], v[120:123]
	v_mfma_f32_16x16x32_bf16 v[112:115], v[150:153], v[190:193], v[112:115]
	v_mfma_f32_16x16x32_bf16 v[104:107], v[158:161], v[190:193], v[104:107]
	v_mfma_f32_16x16x32_bf16 v[96:99], v[150:153], v[198:201], v[96:99]
	v_mfma_f32_16x16x32_bf16 v[88:91], v[158:161], v[198:201], v[88:91]
	v_mfma_f32_16x16x32_bf16 v[80:83], v[150:153], v[206:209], v[80:83]
	v_mfma_f32_16x16x32_bf16 v[72:75], v[158:161], v[206:209], v[72:75]
	v_mfma_f32_16x16x32_bf16 v[124:127], v[154:157], v[186:189], v[124:127]
	v_mfma_f32_16x16x32_bf16 v[120:123], v[162:165], v[186:189], v[120:123]
	v_mfma_f32_16x16x32_bf16 v[112:115], v[154:157], v[194:197], v[112:115]
	v_mfma_f32_16x16x32_bf16 v[104:107], v[162:165], v[194:197], v[104:107]
	v_mfma_f32_16x16x32_bf16 v[96:99], v[154:157], v[202:205], v[96:99]
	v_mfma_f32_16x16x32_bf16 v[88:91], v[162:165], v[202:205], v[88:91]
	v_mfma_f32_16x16x32_bf16 v[80:83], v[154:157], v[210:213], v[80:83]
	v_mfma_f32_16x16x32_bf16 v[72:75], v[162:165], v[210:213], v[72:75]
	v_mfma_f32_16x16x32_bf16 v[116:119], v[166:169], v[182:185], v[116:119]
	v_mfma_f32_16x16x32_bf16 v[108:111], v[174:177], v[182:185], v[108:111]
	v_mfma_f32_16x16x32_bf16 v[100:103], v[166:169], v[190:193], v[100:103]
	v_mfma_f32_16x16x32_bf16 v[92:95], v[174:177], v[190:193], v[92:95]
	v_mfma_f32_16x16x32_bf16 v[84:87], v[166:169], v[198:201], v[84:87]
	v_mfma_f32_16x16x32_bf16 v[76:79], v[174:177], v[198:201], v[76:79]
	v_mfma_f32_16x16x32_bf16 v[68:71], v[166:169], v[206:209], v[68:71]
	v_mfma_f32_16x16x32_bf16 v[64:67], v[174:177], v[206:209], v[64:67]
	v_mfma_f32_16x16x32_bf16 v[116:119], v[170:173], v[186:189], v[116:119]
	v_mfma_f32_16x16x32_bf16 v[108:111], v[178:181], v[186:189], v[108:111]
	v_mfma_f32_16x16x32_bf16 v[100:103], v[170:173], v[194:197], v[100:103]
	v_mfma_f32_16x16x32_bf16 v[92:95], v[178:181], v[194:197], v[92:95]
	v_mfma_f32_16x16x32_bf16 v[84:87], v[170:173], v[202:205], v[84:87]
	v_mfma_f32_16x16x32_bf16 v[76:79], v[178:181], v[202:205], v[76:79]
	v_mfma_f32_16x16x32_bf16 v[68:71], v[170:173], v[210:213], v[68:71]
	v_mfma_f32_16x16x32_bf16 v[64:67], v[178:181], v[210:213], v[64:67]
	s_barrier
	s_add_i32 s61, s49, s40
	v_lshl_add_u64 v[142:143], s[34:35], 0, v[132:133]
	s_mov_b32 m0, s61
	ds_read_b128 v[182:185], v149 offset:16384
	ds_read_b128 v[186:189], v149 offset:17408
	ds_read_b128 v[190:193], v149 offset:18432
	ds_read_b128 v[194:197], v149 offset:19456
	ds_read_b128 v[198:201], v149 offset:20480
	ds_read_b128 v[202:205], v149 offset:21504
	ds_read_b128 v[206:209], v149 offset:22528
	ds_read_b128 v[210:213], v149 offset:23552
	global_load_lds_dwordx4 v[142:143], off
	s_add_i32 m0, s61, 0x2000
	s_add_u32 s62, s34, 0x100000
	v_lshl_add_u64 v[214:215], s[34:35], 0, v[128:129]
	s_addc_u32 s63, s35, 0
	s_add_i32 s61, s50, s40
	global_load_lds_dwordx4 v[214:215], off
	v_lshl_add_u64 v[216:217], s[62:63], 0, v[132:133]
	s_mov_b32 m0, s61
	v_lshl_add_u64 v[218:219], s[36:37], 0, v[130:131]
	global_load_lds_dwordx4 v[216:217], off
	v_lshl_add_u64 v[216:217], s[62:63], 0, v[128:129]
	s_add_i32 m0, s61, 0x2000
	s_nop 0
	global_load_lds_dwordx4 v[216:217], off
	v_lshl_add_u64 v[216:217], s[36:37], 0, v[134:135]
	s_mov_b32 m0, s29
	s_nop 0
	global_load_lds_dwordx4 v[216:217], off
	s_mov_b32 m0, s43
	s_nop 0
	global_load_lds_dwordx4 v[218:219], off
	s_waitcnt vmcnt(8)
	s_waitcnt lgkmcnt(0)
	s_barrier
; #define PG8_STAGE(bufoff, gbase, voff) do { _Pragma("unroll") for (int _i = 0; _i < 2; ++_i) \
;         __builtin_amdgcn_global_load_lds((const unsigned*)((const char*)(gbase) + (voff)[_i]), (PG8_LAS unsigned*)(lds + (bufoff) + ldsw + _i * 8192), 16, 0, 0); } while (0)
; #define PG8_LDA(dst, b, h) do { _Pragma("unroll") for (int m = 0; m < 4; ++m) _Pragma("unroll") for (int k = 0; k < 2; ++k) dst[m][k] = *(const PG8_LAS bf16x8*)(lds + PG8_SA(b, h) + aoff + m * 2048 + k * 1024); } while (0)
; #define PG8_LDB(dst, b, h) do { _Pragma("unroll") for (int n = 0; n < 2; ++n) _Pragma("unroll") for (int k = 0; k < 2; ++k) dst[n][k] = *(const PG8_LAS bf16x8*)(lds + PG8_SB(b, h) + boff + n * 2048 + k * 1024); } while (0)
; #define PG8_MMA(ai, bj, At, Bt) do { __builtin_amdgcn_s_setprio(1); _Pragma("unroll") for (int m = 0; m < 4; ++m) _Pragma("unroll") for (int n = 0; n < 2; ++n) _Pragma("unroll") for (int k = 0; k < 2; ++k) \
;         acc[ai][bj][m][n] = __builtin_amdgcn_mfma_f32_16x16x32_bf16(Bt[n][k], At[m][k], acc[ai][bj][m][n], 0, 0, 0); __builtin_amdgcn_s_setprio(0); } while (0)
; #define PG8_WAIT_V(n) asm volatile("s_waitcnt vmcnt(" #n ")" ::: "memory")
; #define PG8_WAIT_L(n) asm volatile("s_waitcnt lgkmcnt(" #n ")" ::: "memory")
; #define PG8_BAR __builtin_amdgcn_s_barrier()
; #define PG8_SCHED __builtin_amdgcn_sched_barrier(0)
; template <class Epi, class Sched, bool ALIGN_EPI = false, bool SP2 = false>
; __device__ __forceinline__ void gemm_phase(PG8_LAS unsigned char* lds, const Gemm g, const Sched& S, const Epi& E, int tid_in) {
;     ...
;             PG8_LDA(At, 0, 1); PG8_STAGE(PG8_SB(0, 0), b2, voffB); PG8_STAGE(PG8_SB(0, 1), b2 + hstep, voffB); PG8_STAGE(PG8_SA(0, 0), a2, voffA);
;             PG8_WAIT_V(8); PG8_WAIT_L(0); PG8_BAR; PG8_MMA(1, 0, At, B0); PG8_MMA(1, 1, At, B1); PG8_BAR; PG8_SCHED;
;             PG8_LDB(B0, 1, 0); PG8_LDB(B1, 1, 1); PG8_SCHED; PG8_LDA(At, 1, 0); PG8_STAGE(PG8_SA(0, 1), a2 + hstep, voffA);
;             PG8_WAIT_V(8); PG8_WAIT_L(0); PG8_BAR; PG8_MMA(0, 0, At, B0); PG8_MMA(0, 1, At, B1); PG8_BAR; PG8_SCHED;
	s_waitcnt lgkmcnt(0)
	v_mfma_f32_16x16x32_bf16 v[60:63], v[150:153], v[182:185], v[60:63]
	v_mfma_f32_16x16x32_bf16 v[56:59], v[158:161], v[182:185], v[56:59]
	v_mfma_f32_16x16x32_bf16 v[48:51], v[150:153], v[190:193], v[48:51]
	v_mfma_f32_16x16x32_bf16 v[40:43], v[158:161], v[190:193], v[40:43]
	v_mfma_f32_16x16x32_bf16 v[32:35], v[150:153], v[198:201], v[32:35]
	v_mfma_f32_16x16x32_bf16 v[24:27], v[158:161], v[198:201], v[24:27]
	v_mfma_f32_16x16x32_bf16 v[16:19], v[150:153], v[206:209], v[16:19]
	v_mfma_f32_16x16x32_bf16 v[8:11], v[158:161], v[206:209], v[8:11]
	v_mfma_f32_16x16x32_bf16 v[60:63], v[154:157], v[186:189], v[60:63]
	v_mfma_f32_16x16x32_bf16 v[56:59], v[162:165], v[186:189], v[56:59]
	v_mfma_f32_16x16x32_bf16 v[48:51], v[154:157], v[194:197], v[48:51]
	v_mfma_f32_16x16x32_bf16 v[40:43], v[162:165], v[194:197], v[40:43]
	v_mfma_f32_16x16x32_bf16 v[32:35], v[154:157], v[202:205], v[32:35]
	v_mfma_f32_16x16x32_bf16 v[24:27], v[162:165], v[202:205], v[24:27]
	v_mfma_f32_16x16x32_bf16 v[16:19], v[154:157], v[210:213], v[16:19]
	v_mfma_f32_16x16x32_bf16 v[8:11], v[162:165], v[210:213], v[8:11]
	v_mfma_f32_16x16x32_bf16 v[52:55], v[166:169], v[182:185], v[52:55]
	v_mfma_f32_16x16x32_bf16 v[44:47], v[174:177], v[182:185], v[44:47]
	v_mfma_f32_16x16x32_bf16 v[36:39], v[166:169], v[190:193], v[36:39]
	v_mfma_f32_16x16x32_bf16 v[28:31], v[174:177], v[190:193], v[28:31]
	v_mfma_f32_16x16x32_bf16 v[20:23], v[166:169], v[198:201], v[20:23]
	v_mfma_f32_16x16x32_bf16 v[12:15], v[174:177], v[198:201], v[12:15]
	v_mfma_f32_16x16x32_bf16 v[4:7], v[166:169], v[206:209], v[4:7]
	v_mfma_f32_16x16x32_bf16 v[0:3], v[174:177], v[206:209], v[0:3]
	v_mfma_f32_16x16x32_bf16 v[52:55], v[170:173], v[186:189], v[52:55]
	v_mfma_f32_16x16x32_bf16 v[44:47], v[178:181], v[186:189], v[44:47]
	v_mfma_f32_16x16x32_bf16 v[36:39], v[170:173], v[194:197], v[36:39]
	v_mfma_f32_16x16x32_bf16 v[28:31], v[178:181], v[194:197], v[28:31]
	v_mfma_f32_16x16x32_bf16 v[20:23], v[170:173], v[202:205], v[20:23]
	v_mfma_f32_16x16x32_bf16 v[12:15], v[178:181], v[202:205], v[12:15]
	v_mfma_f32_16x16x32_bf16 v[4:7], v[170:173], v[210:213], v[4:7]
	v_mfma_f32_16x16x32_bf16 v[0:3], v[178:181], v[210:213], v[0:3]
	s_barrier
	s_add_i32 s61, 0, 0x18000
	s_add_i32 s62, 0, 0x1c000
	v_add_u32_e32 v162, s61, v145
	v_add_u32_e32 v178, s62, v145
	ds_read_b128 v[150:153], v162
	ds_read_b128 v[154:157], v162 offset:1024
	ds_read_b128 v[158:161], v162 offset:2048
	ds_read_b128 v[162:165], v162 offset:3072
	ds_read_b128 v[166:169], v178
	ds_read_b128 v[170:173], v178 offset:1024
	ds_read_b128 v[174:177], v178 offset:2048
	ds_read_b128 v[178:181], v178 offset:3072
	s_add_u32 s36, s36, 0x100000
	s_addc_u32 s37, s37, 0
	s_mov_b32 m0, s44
	v_lshl_add_u64 v[220:221], s[36:37], 0, v[134:135]
	ds_read_b128 v[182:185], v149 offset:32768
	ds_read_b128 v[186:189], v149 offset:33792
	ds_read_b128 v[190:193], v149 offset:34816
	ds_read_b128 v[194:197], v149 offset:35840
	ds_read_b128 v[198:201], v149 offset:36864
	ds_read_b128 v[202:205], v149 offset:37888
	ds_read_b128 v[206:209], v149 offset:38912
	ds_read_b128 v[210:213], v149 offset:39936
	global_load_lds_dwordx4 v[220:221], off
	v_lshl_add_u64 v[220:221], s[36:37], 0, v[130:131]
	s_mov_b32 m0, s45
	s_nop 0
	global_load_lds_dwordx4 v[220:221], off
	s_waitcnt vmcnt(8)
	s_waitcnt lgkmcnt(0)
	s_barrier
	s_waitcnt lgkmcnt(0)
	v_mfma_f32_16x16x32_bf16 v[124:127], v[150:153], v[182:185], v[124:127]
	v_mfma_f32_16x16x32_bf16 v[120:123], v[158:161], v[182:185], v[120:123]
	v_mfma_f32_16x16x32_bf16 v[112:115], v[150:153], v[190:193], v[112:115]
	v_mfma_f32_16x16x32_bf16 v[104:107], v[158:161], v[190:193], v[104:107]
	v_mfma_f32_16x16x32_bf16 v[96:99], v[150:153], v[198:201], v[96:99]
	v_mfma_f32_16x16x32_bf16 v[88:91], v[158:161], v[198:201], v[88:91]
	v_mfma_f32_16x16x32_bf16 v[80:83], v[150:153], v[206:209], v[80:83]
	v_mfma_f32_16x16x32_bf16 v[72:75], v[158:161], v[206:209], v[72:75]
	v_mfma_f32_16x16x32_bf16 v[124:127], v[154:157], v[186:189], v[124:127]
	v_mfma_f32_16x16x32_bf16 v[120:123], v[162:165], v[186:189], v[120:123]
	v_mfma_f32_16x16x32_bf16 v[112:115], v[154:157], v[194:197], v[112:115]
	v_mfma_f32_16x16x32_bf16 v[104:107], v[162:165], v[194:197], v[104:107]
	v_mfma_f32_16x16x32_bf16 v[96:99], v[154:157], v[202:205], v[96:99]
	v_mfma_f32_16x16x32_bf16 v[88:91], v[162:165], v[202:205], v[88:91]
	v_mfma_f32_16x16x32_bf16 v[80:83], v[154:157], v[210:213], v[80:83]
	v_mfma_f32_16x16x32_bf16 v[72:75], v[162:165], v[210:213], v[72:75]
	v_mfma_f32_16x16x32_bf16 v[116:119], v[166:169], v[182:185], v[116:119]
	v_mfma_f32_16x16x32_bf16 v[108:111], v[174:177], v[182:185], v[108:111]
	v_mfma_f32_16x16x32_bf16 v[100:103], v[166:169], v[190:193], v[100:103]
	v_mfma_f32_16x16x32_bf16 v[92:95], v[174:177], v[190:193], v[92:95]
	v_mfma_f32_16x16x32_bf16 v[84:87], v[166:169], v[198:201], v[84:87]
	v_mfma_f32_16x16x32_bf16 v[76:79], v[174:177], v[198:201], v[76:79]
	v_mfma_f32_16x16x32_bf16 v[68:71], v[166:169], v[206:209], v[68:71]
	v_mfma_f32_16x16x32_bf16 v[64:67], v[174:177], v[206:209], v[64:67]
	v_mfma_f32_16x16x32_bf16 v[116:119], v[170:173], v[186:189], v[116:119]
	v_mfma_f32_16x16x32_bf16 v[108:111], v[178:181], v[186:189], v[108:111]
	v_mfma_f32_16x16x32_bf16 v[100:103], v[170:173], v[194:197], v[100:103]
	v_mfma_f32_16x16x32_bf16 v[92:95], v[178:181], v[194:197], v[92:95]
	v_mfma_f32_16x16x32_bf16 v[84:87], v[170:173], v[202:205], v[84:87]
	v_mfma_f32_16x16x32_bf16 v[76:79], v[178:181], v[202:205], v[76:79]
	v_mfma_f32_16x16x32_bf16 v[68:71], v[170:173], v[210:213], v[68:71]
	v_mfma_f32_16x16x32_bf16 v[64:67], v[178:181], v[210:213], v[64:67]
	s_barrier
; #define PG8_STAGE(bufoff, gbase, voff) do { _Pragma("unroll") for (int _i = 0; _i < 2; ++_i) \
;         __builtin_amdgcn_global_load_lds((const unsigned*)((const char*)(gbase) + (voff)[_i]), (PG8_LAS unsigned*)(lds + (bufoff) + ldsw + _i * 8192), 16, 0, 0); } while (0)
; #define PG8_LDA(dst, b, h) do { _Pragma("unroll") for (int m = 0; m < 4; ++m) _Pragma("unroll") for (int k = 0; k < 2; ++k) dst[m][k] = *(const PG8_LAS bf16x8*)(lds + PG8_SA(b, h) + aoff + m * 2048 + k * 1024); } while (0)
; #define PG8_MMA(ai, bj, At, Bt) do { __builtin_amdgcn_s_setprio(1); _Pragma("unroll") for (int m = 0; m < 4; ++m) _Pragma("unroll") for (int n = 0; n < 2; ++n) _Pragma("unroll") for (int k = 0; k < 2; ++k) \
;         acc[ai][bj][m][n] = __builtin_amdgcn_mfma_f32_16x16x32_bf16(Bt[n][k], At[m][k], acc[ai][bj][m][n], 0, 0, 0); __builtin_amdgcn_s_setprio(0); } while (0)
; #define PG8_WAIT_V(n) asm volatile("s_waitcnt vmcnt(" #n ")" ::: "memory")
; #define PG8_WAIT_L(n) asm volatile("s_waitcnt lgkmcnt(" #n ")" ::: "memory")
; #define PG8_BAR __builtin_amdgcn_s_barrier()
; #define PG8_SCHED __builtin_amdgcn_sched_barrier(0)
; template <class Epi, class Sched, bool ALIGN_EPI = false, bool SP2 = false>
; __device__ __forceinline__ void gemm_phase(PG8_LAS unsigned char* lds, const Gemm g, const Sched& S, const Epi& E, int tid_in) {
;     ...
;             PG8_LDA(At, 1, 1); PG8_STAGE(PG8_SB(1, 0), b3, voffB); PG8_STAGE(PG8_SB(1, 1), b3 + hstep, voffB); PG8_STAGE(PG8_SA(1, 0), a3, voffA);
;             PG8_WAIT_V(8); PG8_WAIT_L(0); PG8_BAR; PG8_MMA(1, 0, At, B0); PG8_MMA(1, 1, At, B1); PG8_BAR; PG8_SCHED;
	s_add_i32 s36, s61, s40
	v_lshl_add_u64 v[142:143], v[142:143], 0, s[6:7]
	s_mov_b32 m0, s36
	ds_read_b128 v[182:185], v149 offset:49152
	ds_read_b128 v[186:189], v149 offset:50176
	ds_read_b128 v[190:193], v149 offset:51200
	ds_read_b128 v[194:197], v149 offset:52224
	ds_read_b128 v[198:201], v149 offset:53248
	ds_read_b128 v[202:205], v149 offset:54272
	ds_read_b128 v[206:209], v149 offset:55296
	ds_read_b128 v[210:213], v149 offset:56320
	global_load_lds_dwordx4 v[142:143], off
	s_add_i32 m0, s36, 0x2000
	s_add_u32 s34, s34, 0x100080
	v_lshl_add_u64 v[142:143], v[214:215], 0, s[6:7]
	s_addc_u32 s35, s35, 0
	s_add_i32 s36, s62, s40
	global_load_lds_dwordx4 v[142:143], off
	v_lshl_add_u64 v[142:143], s[34:35], 0, v[132:133]
	s_mov_b32 m0, s36
	s_nop 0
	global_load_lds_dwordx4 v[142:143], off
	v_lshl_add_u64 v[142:143], s[34:35], 0, v[128:129]
	s_add_i32 m0, s36, 0x2000
	s_nop 0
	global_load_lds_dwordx4 v[142:143], off
	v_lshl_add_u64 v[142:143], v[216:217], 0, s[6:7]
	s_mov_b32 m0, s47
	s_nop 0
	global_load_lds_dwordx4 v[142:143], off
	v_lshl_add_u64 v[142:143], v[218:219], 0, s[6:7]
	s_mov_b32 m0, s48
	s_nop 0
	global_load_lds_dwordx4 v[142:143], off
	s_waitcnt vmcnt(8)
	s_waitcnt lgkmcnt(0)
	s_barrier
	s_waitcnt lgkmcnt(0)
	v_mfma_f32_16x16x32_bf16 v[60:63], v[150:153], v[182:185], v[60:63]
	v_mfma_f32_16x16x32_bf16 v[56:59], v[158:161], v[182:185], v[56:59]
	v_mfma_f32_16x16x32_bf16 v[48:51], v[150:153], v[190:193], v[48:51]
	v_mfma_f32_16x16x32_bf16 v[40:43], v[158:161], v[190:193], v[40:43]
	v_mfma_f32_16x16x32_bf16 v[32:35], v[150:153], v[198:201], v[32:35]
	v_mfma_f32_16x16x32_bf16 v[24:27], v[158:161], v[198:201], v[24:27]
	v_mfma_f32_16x16x32_bf16 v[16:19], v[150:153], v[206:209], v[16:19]
	v_mfma_f32_16x16x32_bf16 v[8:11], v[158:161], v[206:209], v[8:11]
	v_mfma_f32_16x16x32_bf16 v[60:63], v[154:157], v[186:189], v[60:63]
	v_mfma_f32_16x16x32_bf16 v[56:59], v[162:165], v[186:189], v[56:59]
	v_mfma_f32_16x16x32_bf16 v[48:51], v[154:157], v[194:197], v[48:51]
	v_mfma_f32_16x16x32_bf16 v[40:43], v[162:165], v[194:197], v[40:43]
	v_mfma_f32_16x16x32_bf16 v[32:35], v[154:157], v[202:205], v[32:35]
	v_mfma_f32_16x16x32_bf16 v[24:27], v[162:165], v[202:205], v[24:27]
	v_mfma_f32_16x16x32_bf16 v[16:19], v[154:157], v[210:213], v[16:19]
	v_mfma_f32_16x16x32_bf16 v[8:11], v[162:165], v[210:213], v[8:11]
	v_mfma_f32_16x16x32_bf16 v[52:55], v[166:169], v[182:185], v[52:55]
	v_mfma_f32_16x16x32_bf16 v[44:47], v[174:177], v[182:185], v[44:47]
	v_mfma_f32_16x16x32_bf16 v[36:39], v[166:169], v[190:193], v[36:39]
	v_mfma_f32_16x16x32_bf16 v[28:31], v[174:177], v[190:193], v[28:31]
	v_mfma_f32_16x16x32_bf16 v[20:23], v[166:169], v[198:201], v[20:23]
	v_mfma_f32_16x16x32_bf16 v[12:15], v[174:177], v[198:201], v[12:15]
	v_mfma_f32_16x16x32_bf16 v[4:7], v[166:169], v[206:209], v[4:7]
	v_mfma_f32_16x16x32_bf16 v[0:3], v[174:177], v[206:209], v[0:3]
	v_mfma_f32_16x16x32_bf16 v[52:55], v[170:173], v[186:189], v[52:55]
	v_mfma_f32_16x16x32_bf16 v[44:47], v[178:181], v[186:189], v[44:47]
	v_mfma_f32_16x16x32_bf16 v[36:39], v[170:173], v[194:197], v[36:39]
	v_mfma_f32_16x16x32_bf16 v[28:31], v[178:181], v[194:197], v[28:31]
	v_mfma_f32_16x16x32_bf16 v[20:23], v[170:173], v[202:205], v[20:23]
	v_mfma_f32_16x16x32_bf16 v[12:15], v[178:181], v[202:205], v[12:15]
	v_mfma_f32_16x16x32_bf16 v[4:7], v[170:173], v[210:213], v[4:7]
	v_mfma_f32_16x16x32_bf16 v[0:3], v[178:181], v[210:213], v[0:3]
	s_barrier
	s_add_i32 s60, s60, 2
	s_add_u32 s30, s30, 0x100
	s_addc_u32 s31, s31, 0
	s_add_u32 s58, s58, 0x100
	s_addc_u32 s59, s59, 0
	s_cmp_gt_u32 s60, 61
	s_cbranch_scc0 .LBB0_1551
	s_and_b64 vcc, exec, s[8:9]
	s_cbranch_vccz .LBB0_1554
	s_barrier

; #define PG8_WAIT_V(n) asm volatile("s_waitcnt vmcnt(" #n ")" ::: "memory")
; #define PG8_BAR __builtin_amdgcn_s_barrier()
; template <class Epi, class Sched, bool ALIGN_EPI = false, bool SP2 = false>
; __device__ __forceinline__ void gemm_phase(PG8_LAS unsigned char* lds, const Gemm g, const Sched& S, const Epi& E, int tid_in) {
;     ...
;     PG8_WAIT_V(0);
;     if constexpr (!ALIGN_EPI) { if (wr == 0) PG8_BAR; }
;     PG8_BAR;
.LBB0_1557:
	s_setprio 0
	v_readlane_b32 s52, v253, 46
	s_waitcnt vmcnt(0)
	v_readlane_b32 s66, v253, 60
	v_readlane_b32 s67, v253, 61
	v_readlane_b32 s54, v253, 48
	v_readlane_b32 s55, v253, 49
	v_readlane_b32 s56, v253, 50
	v_readlane_b32 s57, v253, 51
	v_readlane_b32 s64, v253, 58
	v_readlane_b32 s65, v253, 59
	s_mov_b64 s[94:95], s[66:67]
	s_mov_b64 s[92:93], s[64:65]
	s_mov_b64 s[82:83], s[54:55]
	s_mov_b64 s[84:85], s[56:57]
	s_barrier
	v_readlane_b32 s53, v253, 47
	v_readlane_b32 s58, v253, 52
	v_readlane_b32 s59, v253, 53
	v_readlane_b32 s60, v253, 54
	v_readlane_b32 s61, v253, 55
	v_readlane_b32 s62, v253, 56
	v_readlane_b32 s63, v253, 57
